# S5 carry scan rewritten by hand: chunk states staged in LDS via LDS-DMA, scan reads LDS, no vmcnt wait in scan loop
# baseline (speedup 1.0000x reference)
; __device__ __forceinline__ unsigned cvt_pk_bf16(float lo, float hi) { unsigned r; asm volatile("v_cvt_pk_bf16_f32 %0, %1, %2" : "=v"(r) : "v"(lo), "v"(hi)); return r; }
; __device__ __forceinline__ void s5_carry2(const Params& P, int j, int g) {
;     int tid = threadIdx.x; asm volatile("" : "+v"(tid));
;     const int wid = __builtin_amdgcn_readfirstlane(tid >> 6), pp = tid & 63;
;     if (wid < 2) {
;         const int dir = wid; const int idx = ((j * 2 + dir) * 64 + g) * 64 + pp;
;         const f32x2 a32 = *(const f32x2*)(P.ws + WS_A32 + (size_t)idx * 8); const float ar = a32.x, ai = a32.y;
;         const float* zp = (const float*)(P.ws + WS_Z) + (size_t)(g * 256) * 256 + dir * 128 + pp;
;         bf16_t* up = (bf16_t*)(P.ws + WS_U2) + (size_t)g * 256 * 768 + 512 + dir * 128 + pp;
;         float cr = 0.f, cim = 0.f; float zr[8], zi[8], nzr[8], nzi[8];
; #pragma unroll
;         for (int u = 0; u < 8; ++u) { const int n = dir ? (255 - u) : u; zr[u] = zp[(size_t)n * 256]; zi[u] = zp[(size_t)n * 256 + 64]; }
;         for (int s0 = 0; s0 < 256; s0 += 8) {
;             if (s0 + 8 < 256) {
; #pragma unroll
;                 for (int u = 0; u < 8; ++u) { const int n = dir ? (255 - (s0 + 8 + u)) : (s0 + 8 + u); nzr[u] = zp[(size_t)n * 256]; nzi[u] = zp[(size_t)n * 256 + 64]; }
;             }
; #pragma unroll
;             for (int u = 0; u < 8; ++u) { const int n = dir ? (255 - (s0 + u)) : (s0 + u);
;                 up[(size_t)n * 768] = (bf16_t)(cvt_pk_bf16(cr, 0.f) & 0xffffu); up[(size_t)n * 768 + 64] = (bf16_t)(cvt_pk_bf16(cim, 0.f) & 0xffffu);
;                 const float nr = ar * cr - ai * cim + zr[u], ni = ar * cim + ai * cr + zi[u]; cr = nr; cim = ni; }
; #pragma unroll
;             for (int u = 0; u < 8; ++u) { zr[u] = nzr[u]; zi[u] = nzi[u]; }
;         }
;     }
;     __syncthreads();
.LBB0_584:
	v_mov_b32_e32 v1, v200
	s_barrier
	s_waitcnt vmcnt(0)
	s_waitcnt vmcnt(0) lgkmcnt(0)
	s_barrier
	buffer_inv sc1
	s_waitcnt vmcnt(0)
	s_nop 0
	v_readfirstlane_b32 s0, v1
	s_ashr_i32 s1, s0, 6
	v_and_b32_e32 v2, 63, v200
	v_lshrrev_b32_e32 v3, 5, v2
	v_and_b32_e32 v4, 31, v2
	v_lshlrev_b32_e32 v5, 9, v3
	v_lshl_add_u32 v5, v4, 4, v5
	v_mul_u32_u24_e32 v7, 0x3fc00, v3
	v_add_u32_e32 v5, v5, v7
	v_lshlrev_b32_e32 v6, 11, v3
	v_sub_u32_e32 v6, 0x400, v6
	v_readlane_b32 s20, v254, 24
	v_readlane_b32 s21, v254, 27
	s_lshl_b32 s12, s1, 4
	v_mul_lo_u32 v8, v6, s12
	v_add_u32_e32 v10, v8, v5
	v_mov_b32_e32 v9, 0
	v_lshlrev_b32_e32 v11, 7, v6
	s_cmp_gt_i32 s1, 1
	s_cbranch_scc1 .Lcarry_setup_done
	s_lshl_b32 s12, s70, 7
	s_lshl_b32 s23, s1, 6
	s_add_i32 s12, s12, s2
	s_add_i32 s12, s12, s23
	v_lshl_or_b32 v14, s12, 6, v2
	v_mov_b32_e32 v15, 0
	v_readlane_b32 s28, v254, 22
	v_readlane_b32 s29, v254, 23
	s_nop 1
	v_lshl_add_u64 v[14:15], v[14:15], 3, s[28:29]
	global_load_dwordx2 v[16:17], v[14:15], off
	s_lshl_b32 s23, s1, 9
	v_lshl_add_u32 v18, v2, 2, s23
	s_mul_i32 s26, s1, 0x5fb00
	v_lshl_add_u32 v19, v2, 1, s26
	s_mul_i32 s36, s1, 0xfffff400
	s_add_i32 s36, s36, 0x600
	v_readlane_b32 s34, v254, 28
	v_readlane_b32 s35, v254, 29
	v_mov_b32_e32 v20, 0
	v_mov_b32_e32 v21, 0
.Lcarry_setup_done:
	s_mov_b32 s37, 0
.Lcarry_half:
	s_lshl_b32 s13, s1, 14
	v_mov_b32_e32 v8, v10
	s_mov_b32 m0, s13
	v_lshl_add_u64 v[12:13], s[20:21], 0, v[8:9]
	global_load_lds_dwordx4 v[12:13], off
	s_add_i32 s13, s13, 0x400
	v_add_u32_e32 v8, v8, v6
	s_mov_b32 m0, s13
	v_lshl_add_u64 v[12:13], s[20:21], 0, v[8:9]
	global_load_lds_dwordx4 v[12:13], off
	s_add_i32 s13, s13, 0x400
	v_add_u32_e32 v8, v8, v6
	s_mov_b32 m0, s13
	v_lshl_add_u64 v[12:13], s[20:21], 0, v[8:9]
	global_load_lds_dwordx4 v[12:13], off
	s_add_i32 s13, s13, 0x400
	v_add_u32_e32 v8, v8, v6
	s_mov_b32 m0, s13
	v_lshl_add_u64 v[12:13], s[20:21], 0, v[8:9]
	global_load_lds_dwordx4 v[12:13], off
	s_add_i32 s13, s13, 0x400
	v_add_u32_e32 v8, v8, v6
	s_mov_b32 m0, s13
	v_lshl_add_u64 v[12:13], s[20:21], 0, v[8:9]
	global_load_lds_dwordx4 v[12:13], off
	s_add_i32 s13, s13, 0x400
	v_add_u32_e32 v8, v8, v6
	s_mov_b32 m0, s13
	v_lshl_add_u64 v[12:13], s[20:21], 0, v[8:9]
	global_load_lds_dwordx4 v[12:13], off
	s_add_i32 s13, s13, 0x400
	v_add_u32_e32 v8, v8, v6
	s_mov_b32 m0, s13
	v_lshl_add_u64 v[12:13], s[20:21], 0, v[8:9]
	global_load_lds_dwordx4 v[12:13], off
	s_add_i32 s13, s13, 0x400
	v_add_u32_e32 v8, v8, v6
	s_mov_b32 m0, s13
	v_lshl_add_u64 v[12:13], s[20:21], 0, v[8:9]
	global_load_lds_dwordx4 v[12:13], off
	s_add_i32 s13, s13, 0x400
	v_add_u32_e32 v8, v8, v6
	s_mov_b32 m0, s13
	v_lshl_add_u64 v[12:13], s[20:21], 0, v[8:9]
	global_load_lds_dwordx4 v[12:13], off
	s_add_i32 s13, s13, 0x400
	v_add_u32_e32 v8, v8, v6
	s_mov_b32 m0, s13
	v_lshl_add_u64 v[12:13], s[20:21], 0, v[8:9]
	global_load_lds_dwordx4 v[12:13], off
	s_add_i32 s13, s13, 0x400
	v_add_u32_e32 v8, v8, v6
	s_mov_b32 m0, s13
	v_lshl_add_u64 v[12:13], s[20:21], 0, v[8:9]
	global_load_lds_dwordx4 v[12:13], off
	s_add_i32 s13, s13, 0x400
	v_add_u32_e32 v8, v8, v6
	s_mov_b32 m0, s13
	v_lshl_add_u64 v[12:13], s[20:21], 0, v[8:9]
	global_load_lds_dwordx4 v[12:13], off
	s_add_i32 s13, s13, 0x400
	v_add_u32_e32 v8, v8, v6
	s_mov_b32 m0, s13
	v_lshl_add_u64 v[12:13], s[20:21], 0, v[8:9]
	global_load_lds_dwordx4 v[12:13], off
	s_add_i32 s13, s13, 0x400
	v_add_u32_e32 v8, v8, v6
	s_mov_b32 m0, s13
	v_lshl_add_u64 v[12:13], s[20:21], 0, v[8:9]
	global_load_lds_dwordx4 v[12:13], off
	s_add_i32 s13, s13, 0x400
	v_add_u32_e32 v8, v8, v6
	s_mov_b32 m0, s13
	v_lshl_add_u64 v[12:13], s[20:21], 0, v[8:9]
	global_load_lds_dwordx4 v[12:13], off
	s_add_i32 s13, s13, 0x400
	v_add_u32_e32 v8, v8, v6
	s_mov_b32 m0, s13
	v_lshl_add_u64 v[12:13], s[20:21], 0, v[8:9]
	global_load_lds_dwordx4 v[12:13], off
	v_add_u32_e32 v10, v10, v11
	s_waitcnt vmcnt(0)
	s_barrier
	s_cmp_gt_i32 s1, 1
	s_cbranch_scc1 .Lcarry_skip
	v_mov_b32_e32 v28, v18
	ds_read2st64_b32 v[32:33], v28 offset0:0 offset1:1
	ds_read2st64_b32 v[34:35], v28 offset0:4 offset1:5
	ds_read2st64_b32 v[36:37], v28 offset0:8 offset1:9
	ds_read2st64_b32 v[38:39], v28 offset0:12 offset1:13
	ds_read2st64_b32 v[40:41], v28 offset0:16 offset1:17
	ds_read2st64_b32 v[42:43], v28 offset0:20 offset1:21
	ds_read2st64_b32 v[44:45], v28 offset0:24 offset1:25
	ds_read2st64_b32 v[46:47], v28 offset0:28 offset1:29
	s_mov_b32 s12, 0
; __device__ __forceinline__ unsigned cvt_pk_bf16(float lo, float hi) { unsigned r; asm volatile("v_cvt_pk_bf16_f32 %0, %1, %2" : "=v"(r) : "v"(lo), "v"(hi)); return r; }
; __device__ __forceinline__ void s5_carry2(const Params& P, int j, int g) {
;     ...
;         for (int s0 = 0; s0 < 256; s0 += 8) {
;             if (s0 + 8 < 256) {
; #pragma unroll
;                 for (int u = 0; u < 8; ++u) { const int n = dir ? (255 - (s0 + 8 + u)) : (s0 + 8 + u); nzr[u] = zp[(size_t)n * 256]; nzi[u] = zp[(size_t)n * 256 + 64]; }
;             }
; #pragma unroll
;             for (int u = 0; u < 8; ++u) { const int n = dir ? (255 - (s0 + u)) : (s0 + u);
;                 up[(size_t)n * 768] = (bf16_t)(cvt_pk_bf16(cr, 0.f) & 0xffffu); up[(size_t)n * 768 + 64] = (bf16_t)(cvt_pk_bf16(cim, 0.f) & 0xffffu);
;                 const float nr = ar * cr - ai * cim + zr[u], ni = ar * cim + ai * cr + zi[u]; cr = nr; cim = ni; }
; #pragma unroll
;             for (int u = 0; u < 8; ++u) { zr[u] = nzr[u]; zi[u] = nzi[u]; }
;         }
.Lcarry_loop:
	s_waitcnt lgkmcnt(0)
	ds_read2st64_b32 v[48:49], v28 offset0:32 offset1:33
	ds_read2st64_b32 v[50:51], v28 offset0:36 offset1:37
	ds_read2st64_b32 v[52:53], v28 offset0:40 offset1:41
	ds_read2st64_b32 v[54:55], v28 offset0:44 offset1:45
	ds_read2st64_b32 v[56:57], v28 offset0:48 offset1:49
	ds_read2st64_b32 v[58:59], v28 offset0:52 offset1:53
	ds_read2st64_b32 v[60:61], v28 offset0:56 offset1:57
	ds_read2st64_b32 v[62:63], v28 offset0:60 offset1:61
	v_cvt_pk_bf16_f32 v22, v20, v21
	global_store_short v19, v22, s[34:35]
	global_store_short_d16_hi v19, v22, s[34:35] offset:128
	v_fma_f32 v24, v16, v20, v32
	v_fma_f32 v25, v16, v21, v33
	v_add_u32_e32 v19, s36, v19
	v_fma_f32 v26, -v17, v21, v24
	v_fma_f32 v27, v17, v20, v25
	v_cvt_pk_bf16_f32 v23, v26, v27
	global_store_short v19, v23, s[34:35]
	global_store_short_d16_hi v19, v23, s[34:35] offset:128
	v_fma_f32 v24, v16, v26, v34
	v_fma_f32 v25, v16, v27, v35
	v_add_u32_e32 v19, s36, v19
	v_fma_f32 v20, -v17, v27, v24
	v_fma_f32 v21, v17, v26, v25
	v_cvt_pk_bf16_f32 v22, v20, v21
	global_store_short v19, v22, s[34:35]
	global_store_short_d16_hi v19, v22, s[34:35] offset:128
	v_fma_f32 v24, v16, v20, v36
	v_fma_f32 v25, v16, v21, v37
	v_add_u32_e32 v19, s36, v19
	v_fma_f32 v26, -v17, v21, v24
	v_fma_f32 v27, v17, v20, v25
	v_cvt_pk_bf16_f32 v23, v26, v27
	global_store_short v19, v23, s[34:35]
	global_store_short_d16_hi v19, v23, s[34:35] offset:128
	v_fma_f32 v24, v16, v26, v38
	v_fma_f32 v25, v16, v27, v39
	v_add_u32_e32 v19, s36, v19
	v_fma_f32 v20, -v17, v27, v24
	v_fma_f32 v21, v17, v26, v25
	v_cvt_pk_bf16_f32 v22, v20, v21
	global_store_short v19, v22, s[34:35]
	global_store_short_d16_hi v19, v22, s[34:35] offset:128
	v_fma_f32 v24, v16, v20, v40
	v_fma_f32 v25, v16, v21, v41
	v_add_u32_e32 v19, s36, v19
	v_fma_f32 v26, -v17, v21, v24
	v_fma_f32 v27, v17, v20, v25
	v_cvt_pk_bf16_f32 v23, v26, v27
	global_store_short v19, v23, s[34:35]
	global_store_short_d16_hi v19, v23, s[34:35] offset:128
	v_fma_f32 v24, v16, v26, v42
	v_fma_f32 v25, v16, v27, v43
	v_add_u32_e32 v19, s36, v19
	v_fma_f32 v20, -v17, v27, v24
	v_fma_f32 v21, v17, v26, v25
	v_cvt_pk_bf16_f32 v22, v20, v21
	global_store_short v19, v22, s[34:35]
	global_store_short_d16_hi v19, v22, s[34:35] offset:128
	v_fma_f32 v24, v16, v20, v44
	v_fma_f32 v25, v16, v21, v45
	v_add_u32_e32 v19, s36, v19
	v_fma_f32 v26, -v17, v21, v24
	v_fma_f32 v27, v17, v20, v25
	v_cvt_pk_bf16_f32 v23, v26, v27
	global_store_short v19, v23, s[34:35]
	global_store_short_d16_hi v19, v23, s[34:35] offset:128
	v_fma_f32 v24, v16, v26, v46
	v_fma_f32 v25, v16, v27, v47
	v_add_u32_e32 v19, s36, v19
	v_fma_f32 v20, -v17, v27, v24
	v_fma_f32 v21, v17, v26, v25
	s_waitcnt lgkmcnt(0)
	ds_read2st64_b32 v[32:33], v28 offset0:64 offset1:65
	ds_read2st64_b32 v[34:35], v28 offset0:68 offset1:69
	ds_read2st64_b32 v[36:37], v28 offset0:72 offset1:73
	ds_read2st64_b32 v[38:39], v28 offset0:76 offset1:77
	ds_read2st64_b32 v[40:41], v28 offset0:80 offset1:81
	ds_read2st64_b32 v[42:43], v28 offset0:84 offset1:85
	ds_read2st64_b32 v[44:45], v28 offset0:88 offset1:89
	ds_read2st64_b32 v[46:47], v28 offset0:92 offset1:93
	v_cvt_pk_bf16_f32 v22, v20, v21
	global_store_short v19, v22, s[34:35]
	global_store_short_d16_hi v19, v22, s[34:35] offset:128
	v_fma_f32 v24, v16, v20, v48
	v_fma_f32 v25, v16, v21, v49
	v_add_u32_e32 v19, s36, v19
	v_fma_f32 v26, -v17, v21, v24
	v_fma_f32 v27, v17, v20, v25
	v_cvt_pk_bf16_f32 v23, v26, v27
	global_store_short v19, v23, s[34:35]
	global_store_short_d16_hi v19, v23, s[34:35] offset:128
	v_fma_f32 v24, v16, v26, v50
	v_fma_f32 v25, v16, v27, v51
	v_add_u32_e32 v19, s36, v19
	v_fma_f32 v20, -v17, v27, v24
	v_fma_f32 v21, v17, v26, v25
	v_cvt_pk_bf16_f32 v22, v20, v21
	global_store_short v19, v22, s[34:35]
	global_store_short_d16_hi v19, v22, s[34:35] offset:128
	v_fma_f32 v24, v16, v20, v52
	v_fma_f32 v25, v16, v21, v53
	v_add_u32_e32 v19, s36, v19
	v_fma_f32 v26, -v17, v21, v24
	v_fma_f32 v27, v17, v20, v25
	v_cvt_pk_bf16_f32 v23, v26, v27
	global_store_short v19, v23, s[34:35]
	global_store_short_d16_hi v19, v23, s[34:35] offset:128
	v_fma_f32 v24, v16, v26, v54
	v_fma_f32 v25, v16, v27, v55
	v_add_u32_e32 v19, s36, v19
	v_fma_f32 v20, -v17, v27, v24
	v_fma_f32 v21, v17, v26, v25
	v_cvt_pk_bf16_f32 v22, v20, v21
	global_store_short v19, v22, s[34:35]
	global_store_short_d16_hi v19, v22, s[34:35] offset:128
	v_fma_f32 v24, v16, v20, v56
	v_fma_f32 v25, v16, v21, v57
	v_add_u32_e32 v19, s36, v19
	v_fma_f32 v26, -v17, v21, v24
	v_fma_f32 v27, v17, v20, v25
	v_cvt_pk_bf16_f32 v23, v26, v27
	global_store_short v19, v23, s[34:35]
	global_store_short_d16_hi v19, v23, s[34:35] offset:128
	v_fma_f32 v24, v16, v26, v58
	v_fma_f32 v25, v16, v27, v59
	v_add_u32_e32 v19, s36, v19
	v_fma_f32 v20, -v17, v27, v24
	v_fma_f32 v21, v17, v26, v25
	v_cvt_pk_bf16_f32 v22, v20, v21
	global_store_short v19, v22, s[34:35]
	global_store_short_d16_hi v19, v22, s[34:35] offset:128
	v_fma_f32 v24, v16, v20, v60
	v_fma_f32 v25, v16, v21, v61
	v_add_u32_e32 v19, s36, v19
	v_fma_f32 v26, -v17, v21, v24
	v_fma_f32 v27, v17, v20, v25
	v_cvt_pk_bf16_f32 v23, v26, v27
	global_store_short v19, v23, s[34:35]
	global_store_short_d16_hi v19, v23, s[34:35] offset:128
	v_fma_f32 v24, v16, v26, v62
	v_fma_f32 v25, v16, v27, v63
	v_add_u32_e32 v19, s36, v19
	v_fma_f32 v20, -v17, v27, v24
	v_fma_f32 v21, v17, v26, v25
	v_add_u32_e32 v28, 0x4000, v28
	s_add_i32 s12, s12, 1
	s_cmp_lt_u32 s12, 8
	s_cbranch_scc1 .Lcarry_loop
	s_waitcnt lgkmcnt(0)
.Lcarry_skip:
	s_barrier
	s_add_i32 s37, s37, 1
	s_cmp_lt_u32 s37, 2
	s_cbranch_scc1 .Lcarry_half
